# s_setprio 1 during stage C of the scan (all waves), 0 again before the block barrier
# speedup vs baseline: 1.0395x; 1.0040x over previous
.LBB0_933:
	v_lshlrev_b32_e32 v32, 2, v114
	v_add3_u32 v32, s10, v32, v42
	v_and_b32_e32 v116, 7, v113
	ds_write_b32 v32, v43 offset:7020
	s_waitcnt lgkmcnt(0)
	s_barrier
	s_setprio 1
	s_waitcnt vmcnt(0)
	v_lshrrev_b32_e32 v41, 3, v113
	v_lshlrev_b32_e32 v168, 5, v116
	v_mul_u32_u24_e32 v136, 0x104, v41
	v_cmp_lt_u32_e32 vcc, 0, v41
	v_add_u32_e32 v169, v136, v168
	v_mov_b32_e32 v137, 0x104
	v_add_u32_e32 v170, 0x2080, v169
	ds_read_b128 v[178:181], v168 offset:61120
	ds_read_b128 v[182:185], v168 offset:61136
	ds_read2_b32 v[194:195], v170 offset0:0 offset1:1
	ds_read2_b32 v[196:197], v170 offset0:2 offset1:3
	ds_read2_b32 v[198:199], v170 offset0:4 offset1:5
	ds_read2_b32 v[200:201], v170 offset0:6 offset1:7
	ds_read_b128 v[208:211], v168 offset:61376
	ds_read_b128 v[212:215], v168 offset:61392
	ds_read2_b32 v[224:225], v169 offset0:0 offset1:1
	ds_read2_b32 v[226:227], v169 offset0:2 offset1:3
	ds_read2_b32 v[228:229], v169 offset0:4 offset1:5
	ds_read2_b32 v[230:231], v169 offset0:6 offset1:7
	v_mov_b32_e32 v232, 0x3fb8aa3b
	v_mov_b32_e32 v233, 0x3fb8aa3b
	v_cndmask_b32_e32 v137, 0, v137, vcc
	v_cndmask_b32_e32 v171, 0, v232, vcc
	v_mov_b32_e32 v234, 1.0
	v_mov_b32_e32 v235, 1.0
	v_sub_u32_e32 v172, v169, v137
	v_add_u32_e32 v173, 0x1f7c, v168
	v_mul_u32_u24_e32 v174, 0x280, v116
	v_lshrrev_b32_e32 v136, 3, v41
	v_and_b32_e32 v138, 4, v116
	v_xor_b32_e32 v136, v136, v116
	v_lshl_add_u32 v174, v138, 4, v174
	v_and_b32_e32 v136, 3, v136
	v_and_b32_e32 v138, 7, v41
	v_lshl_add_u32 v174, v136, 4, v174
	v_mul_u32_u24_e32 v175, 0x90, v41
	v_lshl_add_u32 v174, v138, 1, v174
	v_lshl_add_u32 v175, v116, 4, v175
	v_lshlrev_b32_e32 v186, 16, v84
	v_and_b32_e32 v187, 0xffff0000, v84
	v_lshlrev_b32_e32 v188, 16, v85
	v_and_b32_e32 v189, 0xffff0000, v85
	v_lshlrev_b32_e32 v190, 16, v86
	v_and_b32_e32 v191, 0xffff0000, v86
	v_lshlrev_b32_e32 v192, 16, v87
	v_and_b32_e32 v193, 0xffff0000, v87
	s_waitcnt lgkmcnt(0)
	ds_read2_b32 v[120:121], v173 offset0:0 offset1:1
	ds_read2_b32 v[122:123], v173 offset0:2 offset1:3
	ds_read2_b32 v[124:125], v173 offset0:4 offset1:5
	ds_read2_b32 v[126:127], v173 offset0:6 offset1:7
	ds_read2_b32 v[128:129], v172 offset0:0 offset1:1
	ds_read2_b32 v[130:131], v172 offset0:2 offset1:3
	ds_read2_b32 v[132:133], v172 offset0:4 offset1:5
	ds_read2_b32 v[134:135], v172 offset0:6 offset1:7
	v_pk_mul_f32 v[178:179], v[178:179], v[186:187]
	v_pk_mul_f32 v[180:181], v[180:181], v[188:189]
	v_pk_mul_f32 v[182:183], v[182:183], v[190:191]
	v_pk_mul_f32 v[184:185], v[184:185], v[192:193]
	v_pk_mul_f32 v[166:167], v[178:179], v[178:179]
	v_pk_fma_f32 v[166:167], v[180:181], v[180:181], v[166:167]
	v_pk_fma_f32 v[166:167], v[182:183], v[182:183], v[166:167]
	v_pk_fma_f32 v[166:167], v[184:185], v[184:185], v[166:167]
	v_pk_add_f32 v[216:217], v[194:195], v[234:235] neg_lo:[0,1] neg_hi:[0,1]
	v_pk_add_f32 v[218:219], v[196:197], v[234:235] neg_lo:[0,1] neg_hi:[0,1]
	v_pk_add_f32 v[220:221], v[198:199], v[234:235] neg_lo:[0,1] neg_hi:[0,1]
	v_pk_add_f32 v[222:223], v[200:201], v[234:235] neg_lo:[0,1] neg_hi:[0,1]
	v_add_f32_e32 v166, v166, v167
	v_pk_fma_f32 v[208:209], v[216:217], v[208:209], v[234:235]
	v_pk_fma_f32 v[210:211], v[218:219], v[210:211], v[234:235]
	v_add_f32_dpp v166, v166, v166 quad_perm:[1,0,3,2] row_mask:0xf bank_mask:0xf bound_ctrl:1
	v_pk_fma_f32 v[212:213], v[220:221], v[212:213], v[234:235]
	v_pk_fma_f32 v[214:215], v[222:223], v[214:215], v[234:235]
	v_add_f32_dpp v166, v166, v166 quad_perm:[2,3,0,1] row_mask:0xf bank_mask:0xf bound_ctrl:1
	v_pk_mul_f32 v[186:187], v[186:187], v[208:209]
	v_pk_mul_f32 v[188:189], v[188:189], v[210:211]
	v_mov_b32_dpp v167, v166 row_half_mirror row_mask:0xf bank_mask:0xf bound_ctrl:1
	v_pk_mul_f32 v[190:191], v[190:191], v[212:213]
	v_pk_mul_f32 v[192:193], v[192:193], v[214:215]
	v_add_f32_e32 v166, v166, v167
	v_add_f32_e32 v166, 0x2b8cbccc, v166
	v_rsq_f32_e32 v166, v166
	s_waitcnt lgkmcnt(0)
	v_pk_mul_f32 v[178:179], v[178:179], v[166:167] op_sel_hi:[1,0]
	v_pk_mul_f32 v[180:181], v[180:181], v[166:167] op_sel_hi:[1,0]
	v_pk_mul_f32 v[182:183], v[182:183], v[166:167] op_sel_hi:[1,0]
	v_pk_mul_f32 v[184:185], v[184:185], v[166:167] op_sel_hi:[1,0]
	v_cmp_eq_u32_e32 vcc, 31, v41
	v_pk_mul_f32 v[216:217], v[178:179], v[194:195]
	v_pk_mul_f32 v[218:219], v[180:181], v[196:197]
	v_pk_mul_f32 v[220:221], v[182:183], v[198:199]
	v_pk_mul_f32 v[222:223], v[184:185], v[200:201]
	s_and_saveexec_b64 s[38:39], vcc
	s_cbranch_execz .Lc_nogc_a
	v_pk_mul_f32 v[194:195], v[120:121], v[232:233]
	v_pk_mul_f32 v[196:197], v[122:123], v[232:233]
	v_pk_mul_f32 v[198:199], v[124:125], v[232:233]
	v_pk_mul_f32 v[200:201], v[126:127], v[232:233]
	v_exp_f32_e64 v194, v194
	v_exp_f32_e64 v195, v195
	v_exp_f32_e64 v196, v196
	v_exp_f32_e64 v197, v197
	v_exp_f32_e64 v198, v198
	v_exp_f32_e64 v199, v199
	v_exp_f32_e64 v200, v200
	v_exp_f32_e64 v201, v201
	ds_write_b128 v168, v[194:197] offset:60864
	ds_write_b128 v168, v[198:201] offset:60880

.LBB0_967:
	s_setprio 0
	s_waitcnt lgkmcnt(0)
	s_barrier
	s_andn2_b64 vcc, exec, s[20:21]
	v_lshlrev_b32_e32 v98, 2, v115
	s_cbranch_vccnz .LBB0_1032
	v_mul_u32_u24_e32 v32, 0x48, v112
	v_lshlrev_b32_e32 v89, 1, v32
	v_add_u32_e32 v88, v89, v96
	ds_read_b128 v[32:35], v88 offset:16640
	v_add3_u32 v94, s42, v89, v96
	ds_read_b128 v[36:39], v94
	ds_read_b128 v[90:93], v88 offset:16672
	ds_read_b128 v[116:119], v94 offset:32
	v_cmp_lt_u32_e64 s[10:11], v112, v98
	s_mov_b64 s[36:37], -1
	s_and_b64 vcc, exec, s[30:31]
	s_waitcnt lgkmcnt(2)
	v_mfma_f32_32x32x16_bf16 v[32:47], v[32:35], v[36:39], 0
	s_waitcnt lgkmcnt(0)
	v_mfma_f32_32x32x16_bf16 v[32:47], v[90:93], v[116:119], v[32:47]
	ds_read_b128 v[90:93], v88 offset:16704
	ds_read_b128 v[116:119], v94 offset:64
	ds_read_b128 v[120:123], v88 offset:16736
	ds_read_b128 v[124:127], v94 offset:96
	v_lshl_add_u32 v88, v112, 1, s43
	s_waitcnt lgkmcnt(2)
	v_mfma_f32_32x32x16_bf16 v[32:47], v[90:93], v[116:119], v[32:47]
	s_waitcnt lgkmcnt(0)
	v_mfma_f32_32x32x16_bf16 v[32:47], v[120:123], v[124:127], v[32:47]
	v_or_b32_e32 v213, 1, v98
	v_or_b32_e32 v214, 2, v98
	v_or_b32_e32 v215, 3, v98
	v_or_b32_e32 v216, 8, v98
	v_or_b32_e32 v217, 9, v98
	v_or_b32_e32 v218, 10, v98
	v_or_b32_e32 v219, 11, v98
	v_or_b32_e32 v220, 16, v98
	v_or_b32_e32 v221, 17, v98
	v_or_b32_e32 v222, 18, v98
	v_or_b32_e32 v223, 19, v98
	v_or_b32_e32 v224, 24, v98
	v_or_b32_e32 v225, 25, v98
	v_or_b32_e32 v226, 26, v98
	v_or_b32_e32 v227, 27, v98
	s_cmp_eq_u64 s[30:31], 0
	s_cbranch_scc1 .Ld_w0_a
	v_mul_u32_u24_e32 v89, 0x50, v98
	v_add_u32_e32 v89, v89, v88
	v_cmp_lt_u32_e32 vcc, v112, v98
	v_cmp_lt_u32_e64 s[10:11], v112, v213
	v_cmp_lt_u32_e64 s[36:37], v112, v214
	v_cndmask_b32_e64 v32, 0, v32, vcc
	v_cmp_lt_u32_e32 vcc, v112, v215
	v_cndmask_b32_e64 v33, 0, v33, s[10:11]
	v_cmp_lt_u32_e64 s[10:11], v112, v216
	v_cvt_pk_bf16_f32 v90, v32, v33
	ds_write_b16 v89, v90 offset:0
	ds_write_b16_d16_hi v89, v90 offset:80
	v_cndmask_b32_e64 v34, 0, v34, s[36:37]
	v_cmp_lt_u32_e64 s[36:37], v112, v217
	v_cndmask_b32_e64 v35, 0, v35, vcc
	v_cmp_lt_u32_e32 vcc, v112, v218
	v_cvt_pk_bf16_f32 v90, v34, v35
	ds_write_b16 v89, v90 offset:160
	ds_write_b16_d16_hi v89, v90 offset:240
	v_cndmask_b32_e64 v36, 0, v36, s[10:11]
	v_cmp_lt_u32_e64 s[10:11], v112, v219
	v_cndmask_b32_e64 v37, 0, v37, s[36:37]
	v_cmp_lt_u32_e64 s[36:37], v112, v220
	v_cvt_pk_bf16_f32 v90, v36, v37
	ds_write_b16 v89, v90 offset:640
	ds_write_b16_d16_hi v89, v90 offset:720
	v_cndmask_b32_e64 v38, 0, v38, vcc
	v_cmp_lt_u32_e32 vcc, v112, v221
	v_cndmask_b32_e64 v39, 0, v39, s[10:11]
	v_cmp_lt_u32_e64 s[10:11], v112, v222
	v_cvt_pk_bf16_f32 v90, v38, v39
	ds_write_b16 v89, v90 offset:800
	ds_write_b16_d16_hi v89, v90 offset:880
	v_cndmask_b32_e64 v40, 0, v40, s[36:37]
	v_cmp_lt_u32_e64 s[36:37], v112, v223
	v_cndmask_b32_e64 v41, 0, v41, vcc
	v_cmp_lt_u32_e32 vcc, v112, v224
	v_cvt_pk_bf16_f32 v90, v40, v41
	ds_write_b16 v89, v90 offset:1280
	ds_write_b16_d16_hi v89, v90 offset:1360
	v_cndmask_b32_e64 v42, 0, v42, s[10:11]
	v_cmp_lt_u32_e64 s[10:11], v112, v225
	v_cndmask_b32_e64 v43, 0, v43, s[36:37]
	v_cmp_lt_u32_e64 s[36:37], v112, v226
	v_cvt_pk_bf16_f32 v90, v42, v43
	ds_write_b16 v89, v90 offset:1440
	ds_write_b16_d16_hi v89, v90 offset:1520
	v_cndmask_b32_e64 v44, 0, v44, vcc
	v_cmp_lt_u32_e32 vcc, v112, v227
	v_cndmask_b32_e64 v45, 0, v45, s[10:11]
	v_cvt_pk_bf16_f32 v90, v44, v45
	ds_write_b16 v89, v90 offset:1920
	ds_write_b16_d16_hi v89, v90 offset:2000
	v_cndmask_b32_e64 v46, 0, v46, s[36:37]
	v_cndmask_b32_e64 v47, 0, v47, vcc
	v_cvt_pk_bf16_f32 v90, v46, v47
	ds_write_b16 v89, v90 offset:2080
	ds_write_b16_d16_hi v89, v90 offset:2160
	s_branch .Ld_done_a

.La_join_b:
	s_waitcnt lgkmcnt(0)
	s_barrier
	s_setprio 1
	s_waitcnt vmcnt(0)
	v_lshrrev_b32_e32 v72, 3, v141
	v_lshlrev_b32_e32 v50, 5, v73
	v_mul_u32_u24_e32 v161, 0x104, v72
	v_cmp_lt_u32_e32 vcc, 0, v72
	v_add_u32_e32 v68, v161, v50
	v_mov_b32_e32 v162, 0x104
	v_add_u32_e32 v69, 0xf200, v68
	ds_read_b128 v[214:217], v50 offset:61120
	ds_read_b128 v[218:221], v50 offset:61136
	ds_read2_b32 v[34:35], v69 offset0:0 offset1:1
	ds_read2_b32 v[36:37], v69 offset0:2 offset1:3
	ds_read2_b32 v[38:39], v69 offset0:4 offset1:5
	ds_read2_b32 v[40:41], v69 offset0:6 offset1:7
	ds_read_b128 v[42:45], v50 offset:61376
	ds_read_b128 v[46:49], v50 offset:61392
	ds_read2_b32 v[60:61], v68 offset0:0 offset1:1
	ds_read2_b32 v[62:63], v68 offset0:2 offset1:3
	ds_read2_b32 v[64:65], v68 offset0:4 offset1:5
	ds_read2_b32 v[66:67], v68 offset0:6 offset1:7
	v_mov_b32_e32 v230, 0x3fb8aa3b
	v_mov_b32_e32 v231, 0x3fb8aa3b
	v_cndmask_b32_e32 v162, 0, v162, vcc
	v_cndmask_b32_e32 v143, 0, v230, vcc
	v_mov_b32_e32 v232, 1.0
	v_mov_b32_e32 v233, 1.0
	v_sub_u32_e32 v145, v68, v162
	v_add_u32_e32 v158, 0x1f7c, v50
	v_mul_u32_u24_e32 v159, 0x280, v73
	v_lshrrev_b32_e32 v161, 3, v72
	v_and_b32_e32 v163, 4, v73
	v_xor_b32_e32 v161, v161, v73
	v_lshl_add_u32 v159, v163, 4, v159
	v_and_b32_e32 v161, 3, v161
	v_and_b32_e32 v163, 7, v72
	v_lshl_add_u32 v159, v161, 4, v159
	v_mul_u32_u24_e32 v160, 0x90, v72
	v_lshl_add_u32 v159, v163, 1, v159
	v_lshl_add_u32 v160, v73, 4, v160
	v_lshlrev_b32_e32 v222, 16, v122
	v_and_b32_e32 v223, 0xffff0000, v122
	v_lshlrev_b32_e32 v224, 16, v123
	v_and_b32_e32 v225, 0xffff0000, v123
	v_lshlrev_b32_e32 v226, 16, v124
	v_and_b32_e32 v227, 0xffff0000, v124
	v_lshlrev_b32_e32 v228, 16, v125
	v_and_b32_e32 v229, 0xffff0000, v125
	s_waitcnt lgkmcnt(0)
	ds_read2_b32 v[74:75], v158 offset0:0 offset1:1
	ds_read2_b32 v[76:77], v158 offset0:2 offset1:3
	ds_read2_b32 v[78:79], v158 offset0:4 offset1:5
	ds_read2_b32 v[80:81], v158 offset0:6 offset1:7
	ds_read2_b32 v[126:127], v145 offset0:0 offset1:1
	ds_read2_b32 v[128:129], v145 offset0:2 offset1:3
	ds_read2_b32 v[130:131], v145 offset0:4 offset1:5
	ds_read2_b32 v[132:133], v145 offset0:6 offset1:7
	v_pk_mul_f32 v[214:215], v[214:215], v[222:223]
	v_pk_mul_f32 v[216:217], v[216:217], v[224:225]
	v_pk_mul_f32 v[218:219], v[218:219], v[226:227]
	v_pk_mul_f32 v[220:221], v[220:221], v[228:229]
	v_pk_mul_f32 v[234:235], v[214:215], v[214:215]
	v_pk_fma_f32 v[234:235], v[216:217], v[216:217], v[234:235]
	v_pk_fma_f32 v[234:235], v[218:219], v[218:219], v[234:235]
	v_pk_fma_f32 v[234:235], v[220:221], v[220:221], v[234:235]
	v_pk_add_f32 v[52:53], v[34:35], v[232:233] neg_lo:[0,1] neg_hi:[0,1]
	v_pk_add_f32 v[54:55], v[36:37], v[232:233] neg_lo:[0,1] neg_hi:[0,1]
	v_pk_add_f32 v[56:57], v[38:39], v[232:233] neg_lo:[0,1] neg_hi:[0,1]
	v_pk_add_f32 v[58:59], v[40:41], v[232:233] neg_lo:[0,1] neg_hi:[0,1]
	v_add_f32_e32 v234, v234, v235
	v_pk_fma_f32 v[42:43], v[52:53], v[42:43], v[232:233]
	v_pk_fma_f32 v[44:45], v[54:55], v[44:45], v[232:233]
	v_add_f32_dpp v234, v234, v234 quad_perm:[1,0,3,2] row_mask:0xf bank_mask:0xf bound_ctrl:1
	v_pk_fma_f32 v[46:47], v[56:57], v[46:47], v[232:233]
	v_pk_fma_f32 v[48:49], v[58:59], v[48:49], v[232:233]
	v_add_f32_dpp v234, v234, v234 quad_perm:[2,3,0,1] row_mask:0xf bank_mask:0xf bound_ctrl:1
	v_pk_mul_f32 v[222:223], v[222:223], v[42:43]
	v_pk_mul_f32 v[224:225], v[224:225], v[44:45]
	v_mov_b32_dpp v235, v234 row_half_mirror row_mask:0xf bank_mask:0xf bound_ctrl:1
	v_pk_mul_f32 v[226:227], v[226:227], v[46:47]
	v_pk_mul_f32 v[228:229], v[228:229], v[48:49]
	ds_read_b128 v[42:45], v50 offset:61632
	ds_read_b128 v[46:49], v50 offset:61648
	v_add_f32_e32 v234, v234, v235
	v_add_f32_e32 v234, 0x2b8cbccc, v234
	v_rsq_f32_e32 v234, v234
	s_waitcnt lgkmcnt(2)
	v_pk_mul_f32 v[214:215], v[214:215], v[234:235] op_sel_hi:[1,0]
	v_pk_mul_f32 v[216:217], v[216:217], v[234:235] op_sel_hi:[1,0]
	v_pk_mul_f32 v[218:219], v[218:219], v[234:235] op_sel_hi:[1,0]
	v_pk_mul_f32 v[220:221], v[220:221], v[234:235] op_sel_hi:[1,0]
	v_cmp_eq_u32_e32 vcc, 31, v72
	v_pk_mul_f32 v[52:53], v[214:215], v[34:35]
	v_pk_mul_f32 v[54:55], v[216:217], v[36:37]
	v_pk_mul_f32 v[56:57], v[218:219], v[38:39]
	v_pk_mul_f32 v[58:59], v[220:221], v[40:41]
	s_and_saveexec_b64 s[60:61], vcc
	s_cbranch_execz .Lc_nogc_b
	v_pk_mul_f32 v[34:35], v[74:75], v[230:231]
	v_pk_mul_f32 v[36:37], v[76:77], v[230:231]
	v_pk_mul_f32 v[38:39], v[78:79], v[230:231]
	v_pk_mul_f32 v[40:41], v[80:81], v[230:231]
	v_exp_f32_e64 v34, v34
	v_exp_f32_e64 v35, v35
	v_exp_f32_e64 v36, v36
	v_exp_f32_e64 v37, v37
	v_exp_f32_e64 v38, v38
	v_exp_f32_e64 v39, v39
	v_exp_f32_e64 v40, v40
	v_exp_f32_e64 v41, v41
	ds_write_b128 v50, v[34:37] offset:60864
	ds_write_b128 v50, v[38:41] offset:60880

.LBB0_1149:
	s_setprio 0
	v_mul_u32_u24_e32 v34, 0x48, v70
	v_lshlrev_b32_e32 v66, 1, v34
	s_waitcnt lgkmcnt(0)
	s_barrier
	s_cmp_eq_u64 s[8:9], 0
	s_cbranch_scc1 .Lpf_skip_b
	s_cmp_lg_u64 s[10:11], 0
	s_cbranch_scc1 .Lpf_skip_b
	s_add_i32 s12, s94, 32
	s_add_i32 s12, s12, s87
	s_mov_b32 s13, 0xfffff000
	v_lshlrev_b32_e32 v232, 2, v51
	v_xor_b32_e32 v232, 31, v232
	v_or_b32_e32 v232, s12, v232
	v_lshl_add_u32 v232, v232, 12, v144
	global_load_dword v213, v232, s[56:57] sc1
	v_mad_i32_i24 v230, s13, 1, v232
	global_load_dword v214, v230, s[56:57] sc1
	v_mad_i32_i24 v231, s13, 2, v232
	global_load_dword v215, v231, s[56:57] sc1
	v_mad_i32_i24 v229, s13, 3, v232
	global_load_dword v216, v229, s[56:57] sc1
	v_mad_i32_i24 v230, s13, 8, v232
	global_load_dword v217, v230, s[56:57] sc1
	v_mad_i32_i24 v231, s13, 9, v232
	global_load_dword v218, v231, s[56:57] sc1
	v_mad_i32_i24 v229, s13, 10, v232
	global_load_dword v219, v229, s[56:57] sc1
	v_mad_i32_i24 v230, s13, 11, v232
	global_load_dword v220, v230, s[56:57] sc1
	v_mad_i32_i24 v231, s13, 16, v232
	global_load_dword v221, v231, s[56:57] sc1
	v_mad_i32_i24 v229, s13, 17, v232
	global_load_dword v222, v229, s[56:57] sc1
	v_mad_i32_i24 v230, s13, 18, v232
	global_load_dword v223, v230, s[56:57] sc1
	v_mad_i32_i24 v231, s13, 19, v232
	global_load_dword v224, v231, s[56:57] sc1
	v_mad_i32_i24 v229, s13, 24, v232
	global_load_dword v225, v229, s[56:57] sc1
	v_mad_i32_i24 v230, s13, 25, v232
	global_load_dword v226, v230, s[56:57] sc1
	v_mad_i32_i24 v231, s13, 26, v232
	global_load_dword v227, v231, s[56:57] sc1
	v_mad_i32_i24 v229, s13, 27, v232
	global_load_dword v228, v229, s[56:57] sc1

.LBB0_1278:
	s_setprio 0
	v_mul_u32_u24_e32 v34, 0x48, v70
	v_lshlrev_b32_e32 v66, 1, v34
	s_waitcnt lgkmcnt(0)
	s_barrier
	s_cmp_eq_u64 s[8:9], 0
	s_cbranch_scc1 .Lpf_skip_c
	s_cmp_lg_u64 s[10:11], 0
	s_cbranch_scc1 .Lpf_skip_c
	s_add_i32 s12, s89, 32
	s_add_i32 s12, s12, s83
	s_mov_b32 s13, 0xfffff000
	v_lshlrev_b32_e32 v232, 2, v51
	v_xor_b32_e32 v232, 31, v232
	v_or_b32_e32 v232, s12, v232
	v_lshl_add_u32 v232, v232, 12, v144
	global_load_dword v213, v232, s[56:57] sc1
	v_mad_i32_i24 v230, s13, 1, v232
	global_load_dword v214, v230, s[56:57] sc1
	v_mad_i32_i24 v231, s13, 2, v232
	global_load_dword v215, v231, s[56:57] sc1
	v_mad_i32_i24 v229, s13, 3, v232
	global_load_dword v216, v229, s[56:57] sc1
	v_mad_i32_i24 v230, s13, 8, v232
	global_load_dword v217, v230, s[56:57] sc1
	v_mad_i32_i24 v231, s13, 9, v232
	global_load_dword v218, v231, s[56:57] sc1
	v_mad_i32_i24 v229, s13, 10, v232
	global_load_dword v219, v229, s[56:57] sc1
	v_mad_i32_i24 v230, s13, 11, v232
	global_load_dword v220, v230, s[56:57] sc1
	v_mad_i32_i24 v231, s13, 16, v232
	global_load_dword v221, v231, s[56:57] sc1
	v_mad_i32_i24 v229, s13, 17, v232
	global_load_dword v222, v229, s[56:57] sc1
	v_mad_i32_i24 v230, s13, 18, v232
	global_load_dword v223, v230, s[56:57] sc1
	v_mad_i32_i24 v231, s13, 19, v232
	global_load_dword v224, v231, s[56:57] sc1
	v_mad_i32_i24 v229, s13, 24, v232
	global_load_dword v225, v229, s[56:57] sc1
	v_mad_i32_i24 v230, s13, 25, v232
	global_load_dword v226, v230, s[56:57] sc1
	v_mad_i32_i24 v231, s13, 26, v232
	global_load_dword v227, v231, s[56:57] sc1
	v_mad_i32_i24 v229, s13, 27, v232
	global_load_dword v228, v229, s[56:57] sc1
